# non-temporal hints on streaming traffic: final norm loads/stores, scan state loads/stores, s1 state stores
# speedup vs baseline: 1.0001x; 1.0001x over previous
.LBB0_85:
	v_ashrrev_i32_e32 v41, 31, v40
	v_add_u32_e32 v0, s10, v40
	v_lshlrev_b64 v[22:23], 11, v[40:41]
	v_min_i32_e32 v46, 0x801f, v0
	v_lshl_add_u64 v[22:23], v[18:19], 0, v[22:23]
	v_ashrrev_i32_e32 v47, 31, v46
	global_load_dwordx2 v[24:25], v[22:23], off nt
	global_load_dwordx2 v[26:27], v[22:23], off offset:512 nt
	global_load_dwordx2 v[28:29], v[22:23], off offset:1024 nt
	global_load_dwordx2 v[30:31], v[22:23], off offset:1536 nt
	v_lshlrev_b64 v[22:23], 11, v[46:47]
	v_lshl_add_u64 v[22:23], v[18:19], 0, v[22:23]
	global_load_dwordx2 v[32:33], v[22:23], off nt
	global_load_dwordx2 v[42:43], v[22:23], off offset:512 nt
	global_load_dwordx2 v[54:55], v[22:23], off offset:1024 nt
	global_load_dwordx2 v[56:57], v[22:23], off offset:1536 nt
	v_add_u32_e32 v22, s11, v40
	v_min_i32_e32 v22, 0x801f, v22
	v_ashrrev_i32_e32 v23, 31, v22
	v_lshlrev_b64 v[34:35], 11, v[22:23]
	v_lshl_add_u64 v[58:59], v[18:19], 0, v[34:35]
	global_load_dwordx2 v[44:45], v[58:59], off nt
	s_mov_b32 s2, 0x358637bd
	v_lshlrev_b64 v[46:47], 12, v[46:47]
	v_lshl_add_u64 v[46:47], v[20:21], 0, v[46:47]
	v_lshlrev_b64 v[22:23], 12, v[22:23]
	s_waitcnt vmcnt(8)
	v_and_b32_e32 v61, 0xffff0000, v24
	s_waitcnt vmcnt(7)
	v_and_b32_e32 v65, 0xffff0000, v26
	v_lshlrev_b32_e32 v60, 16, v24
	v_lshlrev_b32_e32 v62, 16, v25
	v_and_b32_e32 v63, 0xffff0000, v25
	v_lshlrev_b32_e32 v64, 16, v26
	v_mov_b32_e32 v24, v61
	v_mov_b32_e32 v25, v65
	s_waitcnt vmcnt(6)
	v_and_b32_e32 v69, 0xffff0000, v28
	s_waitcnt vmcnt(5)
	v_and_b32_e32 v73, 0xffff0000, v30
	v_mov_b32_e32 v76, v60
	v_mov_b32_e32 v77, v64
	v_pk_mul_f32 v[88:89], v[24:25], v[24:25]
	s_waitcnt vmcnt(4)
	v_and_b32_e32 v39, 0xffff0000, v32
	s_waitcnt vmcnt(3)
	v_and_b32_e32 v35, 0xffff0000, v42
	v_lshlrev_b32_e32 v66, 16, v27
	v_and_b32_e32 v67, 0xffff0000, v27
	v_mov_b32_e32 v26, v69
	v_mov_b32_e32 v27, v73
	v_lshlrev_b32_e32 v38, 16, v32
	v_lshlrev_b32_e32 v36, 16, v33
	v_and_b32_e32 v37, 0xffff0000, v33
	v_lshlrev_b32_e32 v34, 16, v42
	v_lshlrev_b32_e32 v32, 16, v43
	v_and_b32_e32 v33, 0xffff0000, v43
	v_pk_fma_f32 v[42:43], v[76:77], v[76:77], v[88:89]
	v_mov_b32_e32 v76, v39
	v_mov_b32_e32 v77, v35
	v_lshlrev_b32_e32 v68, 16, v28
	v_lshlrev_b32_e32 v72, 16, v30
	v_lshlrev_b32_e32 v74, 16, v31
	v_and_b32_e32 v75, 0xffff0000, v31
	v_pk_mul_f32 v[90:91], v[26:27], v[26:27]
	s_waitcnt vmcnt(2)
	v_and_b32_e32 v31, 0xffff0000, v54
	s_waitcnt vmcnt(1)
	v_lshlrev_b32_e32 v26, 16, v56
	v_and_b32_e32 v27, 0xffff0000, v56
	v_lshlrev_b32_e32 v24, 16, v57
	v_and_b32_e32 v25, 0xffff0000, v57
	v_mov_b32_e32 v56, v38
	v_mov_b32_e32 v57, v34
	v_pk_mul_f32 v[76:77], v[76:77], v[76:77]
	v_mov_b32_e32 v82, v68
	v_mov_b32_e32 v83, v72
	v_lshlrev_b32_e32 v30, 16, v54
	v_pk_fma_f32 v[56:57], v[56:57], v[56:57], v[76:77]
	v_mov_b32_e32 v76, v31
	v_mov_b32_e32 v77, v27
	v_lshlrev_b32_e32 v70, 16, v29
	v_and_b32_e32 v71, 0xffff0000, v29
	v_mov_b32_e32 v78, v62
	v_mov_b32_e32 v79, v66
	v_lshlrev_b32_e32 v28, 16, v55
	v_and_b32_e32 v29, 0xffff0000, v55
	v_pk_fma_f32 v[54:55], v[82:83], v[82:83], v[90:91]
	v_mov_b32_e32 v82, v36
	v_mov_b32_e32 v83, v32
	v_mov_b32_e32 v90, v30
	v_mov_b32_e32 v91, v26
	v_pk_mul_f32 v[76:77], v[76:77], v[76:77]
	v_mov_b32_e32 v80, v63
	v_mov_b32_e32 v81, v67
	v_mov_b32_e32 v84, v70
	v_mov_b32_e32 v85, v74
	v_mov_b32_e32 v88, v37
	v_mov_b32_e32 v89, v33
	v_pk_fma_f32 v[42:43], v[78:79], v[78:79], v[42:43]
	v_pk_fma_f32 v[56:57], v[82:83], v[82:83], v[56:57]
	v_pk_fma_f32 v[76:77], v[90:91], v[90:91], v[76:77]
	v_mov_b32_e32 v78, v28
	v_mov_b32_e32 v79, v24
	v_mov_b32_e32 v86, v71
	v_mov_b32_e32 v87, v75
	v_pk_fma_f32 v[54:55], v[84:85], v[84:85], v[54:55]
	v_pk_fma_f32 v[42:43], v[80:81], v[80:81], v[42:43]
	v_pk_fma_f32 v[56:57], v[88:89], v[88:89], v[56:57]
	v_mov_b32_e32 v80, v29
	v_mov_b32_e32 v81, v25
	v_pk_fma_f32 v[76:77], v[78:79], v[78:79], v[76:77]
	v_pk_fma_f32 v[54:55], v[86:87], v[86:87], v[54:55]
	v_pk_fma_f32 v[76:77], v[80:81], v[80:81], v[76:77]
	v_mov_b32_e32 v78, v56
	v_mov_b32_e32 v79, v42
	v_mov_b32_e32 v42, v57
	v_pk_add_f32 v[42:43], v[78:79], v[42:43]
	v_mov_b32_e32 v56, v76
	v_mov_b32_e32 v57, v54
	v_pk_add_f32 v[42:43], v[42:43], v[56:57]
	v_mov_b32_e32 v54, v77
	v_pk_add_f32 v[42:43], v[42:43], v[54:55]
	ds_bpermute_b32 v55, v48, v43
	ds_bpermute_b32 v54, v48, v42
	global_load_dwordx2 v[76:77], v[58:59], off offset:512 nt
	global_load_dwordx2 v[78:79], v[58:59], off offset:1024 nt
	v_add_u32_e32 v80, s12, v40
	global_load_dwordx2 v[58:59], v[58:59], off offset:1536 nt
	v_lshlrev_b64 v[88:89], 12, v[40:41]
	s_waitcnt lgkmcnt(0)
	v_pk_add_f32 v[42:43], v[42:43], v[54:55]
	ds_bpermute_b32 v55, v49, v43
	ds_bpermute_b32 v54, v49, v42
	v_mov_b64_e32 v[40:41], s[2:3]
	v_lshl_add_u64 v[88:89], v[20:21], 0, v[88:89]
	s_add_i32 s2, s10, s10
	s_add_i32 s2, s2, s10
	s_waitcnt lgkmcnt(0)
	v_pk_add_f32 v[42:43], v[42:43], v[54:55]
	ds_bpermute_b32 v55, v50, v43
	ds_bpermute_b32 v54, v50, v42
	s_waitcnt lgkmcnt(0)
	v_pk_add_f32 v[42:43], v[42:43], v[54:55]
	ds_bpermute_b32 v55, v51, v43
	ds_bpermute_b32 v54, v51, v42
	s_waitcnt lgkmcnt(0)
	v_pk_add_f32 v[54:55], v[42:43], v[54:55]
	v_min_i32_e32 v42, 0x801f, v80
	v_ashrrev_i32_e32 v43, 31, v42
	v_lshlrev_b64 v[80:81], 11, v[42:43]
	v_lshl_add_u64 v[80:81], v[18:19], 0, v[80:81]
	global_load_dwordx2 v[82:83], v[80:81], off nt
	global_load_dwordx2 v[84:85], v[80:81], off offset:512 nt
	global_load_dwordx2 v[86:87], v[80:81], off offset:1024 nt
	s_nop 0
	global_load_dwordx2 v[80:81], v[80:81], off offset:1536 nt
	ds_bpermute_b32 v57, v52, v55
	ds_bpermute_b32 v56, v52, v54
	s_waitcnt lgkmcnt(0)
	v_pk_add_f32 v[54:55], v[54:55], v[56:57]
	ds_bpermute_b32 v57, v53, v55
	ds_bpermute_b32 v56, v53, v54
	s_waitcnt lgkmcnt(0)
	v_pk_add_f32 v[54:55], v[54:55], v[56:57]
	s_nop 0
	v_pk_fma_f32 v[90:91], v[54:55], s[16:17], v[40:41] op_sel_hi:[1,0,0]
	s_nop 0
	v_mul_f32_e32 v54, 0x4b800000, v91
	v_cmp_gt_f32_e32 vcc, s14, v91
	s_nop 1
	v_cndmask_b32_e32 v54, v91, v54, vcc
	v_rsq_f32_e32 v54, v54
	s_waitcnt vmcnt(1)
	v_and_b32_e32 v91, 0xffff0000, v86
	v_mul_f32_e32 v55, 0x45800000, v54
	v_cndmask_b32_e32 v92, v54, v55, vcc
	v_pk_mul_f32 v[54:55], v[92:93], v[60:61] op_sel_hi:[0,1]
	v_pk_mul_f32 v[56:57], v[92:93], v[62:63] op_sel_hi:[0,1]
	v_pk_mul_f32 v[54:55], v[2:3], v[54:55]
	v_pk_mul_f32 v[56:57], v[4:5], v[56:57]
	global_store_dwordx4 v[88:89], v[54:57], off nt
	v_mul_f32_e32 v60, 0x4b800000, v90
	v_cmp_gt_f32_e32 vcc, s14, v90
	v_pk_mul_f32 v[54:55], v[92:93], v[64:65] op_sel_hi:[0,1]
	v_pk_mul_f32 v[56:57], v[92:93], v[66:67] op_sel_hi:[0,1]
	v_pk_mul_f32 v[54:55], v[6:7], v[54:55]
	v_pk_mul_f32 v[56:57], v[8:9], v[56:57]
	global_store_dwordx4 v[88:89], v[54:57], off offset:1024 nt
	v_cndmask_b32_e32 v60, v90, v60, vcc
	v_and_b32_e32 v61, 0xffff0000, v44
	v_pk_mul_f32 v[54:55], v[92:93], v[68:69] op_sel_hi:[0,1]
	v_pk_mul_f32 v[56:57], v[92:93], v[70:71] op_sel_hi:[0,1]
	v_pk_mul_f32 v[54:55], v[10:11], v[54:55]
	v_pk_mul_f32 v[56:57], v[12:13], v[56:57]
	v_and_b32_e32 v63, 0xffff0000, v76
	global_store_dwordx4 v[88:89], v[54:57], off offset:2048 nt
	v_rsq_f32_e32 v102, v60
	v_lshlrev_b32_e32 v60, 16, v44
	v_pk_mul_f32 v[56:57], v[92:93], v[74:75] op_sel_hi:[0,1]
	v_lshlrev_b32_e32 v62, 16, v76
	v_mov_b32_e32 v74, v61
	v_mov_b32_e32 v75, v63
	v_pk_mul_f32 v[54:55], v[92:93], v[72:73] op_sel_hi:[0,1]
	v_lshlrev_b32_e32 v44, 16, v45
	v_lshlrev_b32_e32 v64, 16, v77
	v_mov_b32_e32 v72, v60
	v_mov_b32_e32 v73, v62
	v_pk_mul_f32 v[74:75], v[74:75], v[74:75]
	v_and_b32_e32 v45, 0xffff0000, v45
	v_and_b32_e32 v65, 0xffff0000, v77
	v_pk_fma_f32 v[72:73], v[72:73], v[72:73], v[74:75]
	v_mov_b32_e32 v74, v44
	v_mov_b32_e32 v75, v64
	v_and_b32_e32 v67, 0xffff0000, v78
	v_and_b32_e32 v71, 0xffff0000, v58
	v_mov_b32_e32 v76, v45
	v_mov_b32_e32 v77, v65
	v_pk_fma_f32 v[72:73], v[74:75], v[74:75], v[72:73]
	v_lshlrev_b32_e32 v66, 16, v78
	v_lshlrev_b32_e32 v70, 16, v58
	v_pk_fma_f32 v[72:73], v[76:77], v[76:77], v[72:73]
	v_mov_b32_e32 v76, v67
	v_mov_b32_e32 v77, v71
	v_lshlrev_b32_e32 v68, 16, v79
	v_lshlrev_b32_e32 v58, 16, v59
	v_mov_b32_e32 v74, v66
	v_mov_b32_e32 v75, v70
	v_pk_mul_f32 v[76:77], v[76:77], v[76:77]
	v_and_b32_e32 v69, 0xffff0000, v79
	v_and_b32_e32 v59, 0xffff0000, v59
	v_pk_fma_f32 v[74:75], v[74:75], v[74:75], v[76:77]
	v_mov_b32_e32 v76, v68
	v_mov_b32_e32 v77, v58
	v_mov_b32_e32 v78, v69
	v_mov_b32_e32 v79, v59
	v_pk_fma_f32 v[74:75], v[76:77], v[76:77], v[74:75]
	v_and_b32_e32 v77, 0xffff0000, v82
	v_pk_fma_f32 v[74:75], v[78:79], v[78:79], v[74:75]
	v_lshlrev_b32_e32 v78, 16, v83
	v_and_b32_e32 v79, 0xffff0000, v83
	v_and_b32_e32 v83, 0xffff0000, v84
	v_lshlrev_b32_e32 v76, 16, v82
	v_lshlrev_b32_e32 v82, 16, v84
	v_mov_b32_e32 v96, v77
	v_mov_b32_e32 v97, v83
	v_lshlrev_b32_e32 v84, 16, v85
	v_mov_b32_e32 v94, v76
	v_mov_b32_e32 v95, v82
	v_pk_mul_f32 v[96:97], v[96:97], v[96:97]
	v_and_b32_e32 v85, 0xffff0000, v85
	v_pk_fma_f32 v[94:95], v[94:95], v[94:95], v[96:97]
	v_mov_b32_e32 v96, v78
	v_mov_b32_e32 v97, v84
	s_waitcnt vmcnt(3)
	v_and_b32_e32 v93, 0xffff0000, v80
	v_mov_b32_e32 v98, v79
	v_mov_b32_e32 v99, v85
	v_pk_fma_f32 v[94:95], v[96:97], v[96:97], v[94:95]
	v_lshlrev_b32_e32 v90, 16, v86
	v_lshlrev_b32_e32 v92, 16, v80
	v_pk_fma_f32 v[94:95], v[98:99], v[98:99], v[94:95]
	v_mov_b32_e32 v98, v91
	v_mov_b32_e32 v99, v93
	v_lshlrev_b32_e32 v86, 16, v87
	v_lshlrev_b32_e32 v80, 16, v81
	v_mov_b32_e32 v96, v90
	v_mov_b32_e32 v97, v92
	v_pk_mul_f32 v[98:99], v[98:99], v[98:99]
	v_and_b32_e32 v87, 0xffff0000, v87
	v_and_b32_e32 v81, 0xffff0000, v81
	v_pk_fma_f32 v[96:97], v[96:97], v[96:97], v[98:99]
	v_mov_b32_e32 v98, v86
	v_mov_b32_e32 v99, v80
	v_mov_b32_e32 v100, v87
	v_mov_b32_e32 v101, v81
	v_pk_fma_f32 v[96:97], v[98:99], v[98:99], v[96:97]
	v_mov_b32_e32 v98, v94
	v_pk_fma_f32 v[96:97], v[100:101], v[100:101], v[96:97]
	v_mov_b32_e32 v99, v72
	v_mov_b32_e32 v72, v95
	v_pk_add_f32 v[72:73], v[98:99], v[72:73]
	v_mov_b32_e32 v94, v96
	v_mov_b32_e32 v95, v74
	v_pk_add_f32 v[72:73], v[72:73], v[94:95]
	v_mov_b32_e32 v74, v97
	v_pk_add_f32 v[72:73], v[72:73], v[74:75]
	ds_bpermute_b32 v75, v48, v73
	ds_bpermute_b32 v74, v48, v72
	v_pk_mul_f32 v[54:55], v[14:15], v[54:55]
	v_pk_mul_f32 v[56:57], v[16:17], v[56:57]
	global_store_dwordx4 v[88:89], v[54:57], off offset:3072 nt
	s_waitcnt lgkmcnt(0)
	v_pk_add_f32 v[72:73], v[72:73], v[74:75]
	ds_bpermute_b32 v75, v49, v73
	ds_bpermute_b32 v74, v49, v72
	v_mul_f32_e32 v54, 0x45800000, v102
	v_cndmask_b32_e32 v88, v102, v54, vcc
	v_pk_mul_f32 v[38:39], v[88:89], v[38:39] op_sel_hi:[0,1]
	v_pk_mul_f32 v[36:37], v[88:89], v[36:37] op_sel_hi:[0,1]
	v_pk_mul_f32 v[54:55], v[2:3], v[38:39]
	v_pk_mul_f32 v[56:57], v[4:5], v[36:37]
	s_waitcnt lgkmcnt(0)
	v_pk_add_f32 v[38:39], v[72:73], v[74:75]
	global_store_dwordx4 v[46:47], v[54:57], off nt
	ds_bpermute_b32 v55, v50, v39
	ds_bpermute_b32 v54, v50, v38
	v_pk_mul_f32 v[32:33], v[88:89], v[32:33] op_sel_hi:[0,1]
	v_pk_mul_f32 v[36:37], v[8:9], v[32:33]
	v_pk_mul_f32 v[34:35], v[88:89], v[34:35] op_sel_hi:[0,1]
	v_pk_mul_f32 v[34:35], v[6:7], v[34:35]
	s_waitcnt lgkmcnt(0)
	v_pk_add_f32 v[32:33], v[38:39], v[54:55]
	ds_bpermute_b32 v39, v51, v33
	ds_bpermute_b32 v38, v51, v32
	global_store_dwordx4 v[46:47], v[34:37], off offset:1024 nt
	v_pk_mul_f32 v[30:31], v[88:89], v[30:31] op_sel_hi:[0,1]
	v_pk_mul_f32 v[28:29], v[88:89], v[28:29] op_sel_hi:[0,1]
	v_pk_mul_f32 v[30:31], v[10:11], v[30:31]
	s_waitcnt lgkmcnt(0)
	v_pk_add_f32 v[34:35], v[32:33], v[38:39]
	ds_bpermute_b32 v37, v52, v35
	ds_bpermute_b32 v36, v52, v34
	v_pk_mul_f32 v[32:33], v[12:13], v[28:29]
	global_store_dwordx4 v[46:47], v[30:33], off offset:2048 nt
	v_pk_mul_f32 v[26:27], v[88:89], v[26:27] op_sel_hi:[0,1]
	v_pk_mul_f32 v[24:25], v[88:89], v[24:25] op_sel_hi:[0,1]
	s_waitcnt lgkmcnt(0)
	v_pk_add_f32 v[30:31], v[34:35], v[36:37]
	ds_bpermute_b32 v33, v53, v31
	ds_bpermute_b32 v32, v53, v30
	v_pk_mul_f32 v[26:27], v[14:15], v[26:27]
	v_pk_mul_f32 v[28:29], v[16:17], v[24:25]
	global_store_dwordx4 v[46:47], v[26:29], off offset:3072 nt
	s_waitcnt lgkmcnt(0)
	v_pk_add_f32 v[24:25], v[30:31], v[32:33]
	s_nop 0
	v_pk_fma_f32 v[26:27], v[24:25], s[16:17], v[40:41] op_sel_hi:[1,0,0]
	v_lshl_add_u64 v[28:29], v[20:21], 0, v[22:23]
	v_mul_f32_e32 v24, 0x4b800000, v27
	v_cmp_gt_f32_e32 vcc, s14, v27
	v_lshlrev_b64 v[22:23], 12, v[42:43]
	v_lshl_add_u64 v[30:31], v[20:21], 0, v[22:23]
	v_cndmask_b32_e32 v24, v27, v24, vcc
	v_rsq_f32_e32 v24, v24
	v_add_u32_e32 v40, s2, v0
	v_mul_f32_e32 v22, 0x45800000, v24
	v_cndmask_b32_e32 v32, v24, v22, vcc
	v_pk_mul_f32 v[22:23], v[32:33], v[60:61] op_sel_hi:[0,1]
	v_pk_mul_f32 v[24:25], v[32:33], v[44:45] op_sel_hi:[0,1]
	v_pk_mul_f32 v[22:23], v[2:3], v[22:23]
	v_pk_mul_f32 v[24:25], v[4:5], v[24:25]
	global_store_dwordx4 v[28:29], v[22:25], off nt
	v_cmp_gt_f32_e32 vcc, s14, v26
	s_nop 0
	v_pk_mul_f32 v[22:23], v[32:33], v[62:63] op_sel_hi:[0,1]
	v_pk_mul_f32 v[24:25], v[32:33], v[64:65] op_sel_hi:[0,1]
	v_pk_mul_f32 v[22:23], v[6:7], v[22:23]
	v_pk_mul_f32 v[24:25], v[8:9], v[24:25]
	global_store_dwordx4 v[28:29], v[22:25], off offset:1024 nt
	s_nop 1
	v_pk_mul_f32 v[22:23], v[32:33], v[66:67] op_sel_hi:[0,1]
	v_pk_mul_f32 v[24:25], v[32:33], v[68:69] op_sel_hi:[0,1]
	v_pk_mul_f32 v[22:23], v[10:11], v[22:23]
	v_pk_mul_f32 v[24:25], v[12:13], v[24:25]
	global_store_dwordx4 v[28:29], v[22:25], off offset:2048 nt
	s_nop 1
	v_mul_f32_e32 v24, 0x4b800000, v26
	v_cndmask_b32_e32 v24, v26, v24, vcc
	v_rsq_f32_e32 v26, v24
	v_pk_mul_f32 v[22:23], v[32:33], v[70:71] op_sel_hi:[0,1]
	v_pk_mul_f32 v[24:25], v[32:33], v[58:59] op_sel_hi:[0,1]
	v_pk_mul_f32 v[22:23], v[14:15], v[22:23]
	v_pk_mul_f32 v[24:25], v[16:17], v[24:25]
	global_store_dwordx4 v[28:29], v[22:25], off offset:3072 nt
	s_nop 1
	v_mul_f32_e32 v22, 0x45800000, v26
	v_cndmask_b32_e32 v26, v26, v22, vcc
	v_pk_mul_f32 v[22:23], v[26:27], v[76:77] op_sel_hi:[0,1]
	v_pk_mul_f32 v[24:25], v[26:27], v[78:79] op_sel_hi:[0,1]
	v_pk_mul_f32 v[22:23], v[2:3], v[22:23]
	v_pk_mul_f32 v[24:25], v[4:5], v[24:25]
	global_store_dwordx4 v[30:31], v[22:25], off nt
	v_cmp_lt_i32_e32 vcc, s13, v40
	s_or_b64 s[8:9], vcc, s[8:9]
	v_pk_mul_f32 v[22:23], v[26:27], v[82:83] op_sel_hi:[0,1]
	v_pk_mul_f32 v[24:25], v[26:27], v[84:85] op_sel_hi:[0,1]
	v_pk_mul_f32 v[22:23], v[6:7], v[22:23]
	v_pk_mul_f32 v[24:25], v[8:9], v[24:25]
	global_store_dwordx4 v[30:31], v[22:25], off offset:1024 nt
	s_nop 1
	v_pk_mul_f32 v[22:23], v[26:27], v[90:91] op_sel_hi:[0,1]
	v_pk_mul_f32 v[24:25], v[26:27], v[86:87] op_sel_hi:[0,1]
	v_pk_mul_f32 v[22:23], v[10:11], v[22:23]
	v_pk_mul_f32 v[24:25], v[12:13], v[24:25]
	global_store_dwordx4 v[30:31], v[22:25], off offset:2048 nt
	s_nop 1
	v_pk_mul_f32 v[22:23], v[26:27], v[92:93] op_sel_hi:[0,1]
	v_pk_mul_f32 v[24:25], v[26:27], v[80:81] op_sel_hi:[0,1]
	v_pk_mul_f32 v[22:23], v[14:15], v[22:23]
	v_pk_mul_f32 v[24:25], v[16:17], v[24:25]
	global_store_dwordx4 v[30:31], v[22:25], off offset:3072 nt
	s_andn2_b64 exec, exec, s[8:9]
	s_cbranch_execnz .LBB0_85

.LBB0_303:
	s_nop 0
	v_lshl_add_u64 v[22:23], s[18:19], 0, v[2:3]
	v_add_co_u32_e32 v24, vcc, 0x1f3e0000, v22
	v_lshl_add_u64 v[18:19], s[18:19], 0, v[4:5]
	s_mov_b64 s[10:11], 0x1b3e0000
	v_addc_co_u32_e32 v25, vcc, 0, v23, vcc
	s_mov_b64 s[16:17], 0x40000
	global_load_dword v26, v[24:25], off
	global_load_dword v28, v[24:25], off offset:32
	global_load_dword v30, v[24:25], off offset:64
	global_load_dword v32, v[24:25], off offset:96
	global_load_dword v34, v[24:25], off offset:128
	global_load_dword v36, v[24:25], off offset:160
	global_load_dword v38, v[24:25], off offset:192
	global_load_dword v40, v[24:25], off offset:224
	global_load_dword v22, v[24:25], off offset:256
	global_load_dword v16, v[24:25], off offset:288
	global_load_dword v14, v[24:25], off offset:320
	global_load_dword v12, v[24:25], off offset:352
	global_load_dword v10, v[24:25], off offset:384
	global_load_dword v8, v[24:25], off offset:416
	global_load_dword v6, v[24:25], off offset:448
	global_load_dword v0, v[24:25], off offset:480
	v_lshl_add_u64 v[80:81], v[18:19], 0, s[10:11]
	v_lshl_add_u64 v[82:83], v[80:81], 0, s[16:17]
	v_lshl_add_u64 v[84:85], v[82:83], 0, s[16:17]
	v_lshl_add_u64 v[86:87], v[84:85], 0, s[16:17]
	v_lshl_add_u64 v[88:89], v[86:87], 0, s[16:17]
	v_lshl_add_u64 v[90:91], v[88:89], 0, s[16:17]
	v_lshl_add_u64 v[92:93], v[90:91], 0, s[16:17]
	v_lshl_add_u64 v[94:95], v[92:93], 0, s[16:17]
	v_lshl_add_u64 v[96:97], v[94:95], 0, s[16:17]
	v_lshl_add_u64 v[98:99], v[96:97], 0, s[16:17]
	v_lshl_add_u64 v[100:101], v[98:99], 0, s[16:17]
	v_lshl_add_u64 v[102:103], v[100:101], 0, s[16:17]
	v_lshl_add_u64 v[104:105], v[102:103], 0, s[16:17]
	v_lshl_add_u64 v[106:107], v[104:105], 0, s[16:17]
	v_lshl_add_u64 v[108:109], v[106:107], 0, s[16:17]
	v_lshl_add_u64 v[110:111], v[108:109], 0, s[16:17]
	global_load_dwordx2 v[48:49], v[80:81], off nt
	global_load_dwordx2 v[50:51], v[82:83], off nt
	global_load_dwordx2 v[52:53], v[84:85], off nt
	global_load_dwordx2 v[54:55], v[86:87], off nt
	global_load_dwordx2 v[56:57], v[88:89], off nt
	global_load_dwordx2 v[58:59], v[90:91], off nt
	global_load_dwordx2 v[60:61], v[92:93], off nt
	global_load_dwordx2 v[62:63], v[94:95], off nt
	global_load_dwordx2 v[64:65], v[96:97], off nt
	global_load_dwordx2 v[66:67], v[98:99], off nt
	global_load_dwordx2 v[68:69], v[100:101], off nt
	global_load_dwordx2 v[70:71], v[102:103], off nt
	global_load_dwordx2 v[72:73], v[104:105], off nt
	global_load_dwordx2 v[74:75], v[106:107], off nt
	global_load_dwordx2 v[76:77], v[108:109], off nt
	global_load_dwordx2 v[78:79], v[110:111], off nt
	s_mov_b64 s[10:11], 0x400000
	v_lshl_add_u64 v[2:3], v[2:3], 0, s[12:13]
	v_lshl_add_u64 v[4:5], v[4:5], 0, s[10:11]
	s_add_i32 s2, s2, 16
	s_cmp_gt_u32 s2, 47
	s_waitcnt vmcnt(15)
	global_store_dwordx2 v[80:81], v[20:21], off nt
	v_pk_fma_f32 v[20:21], v[20:21], v[26:27], v[48:49] op_sel_hi:[1,0,1]
	s_waitcnt vmcnt(15)
	global_store_dwordx2 v[82:83], v[20:21], off nt
	v_pk_fma_f32 v[20:21], v[20:21], v[28:29], v[50:51] op_sel_hi:[1,0,1]
	s_waitcnt vmcnt(15)
	global_store_dwordx2 v[84:85], v[20:21], off nt
	v_pk_fma_f32 v[20:21], v[20:21], v[30:31], v[52:53] op_sel_hi:[1,0,1]
	s_waitcnt vmcnt(15)
	global_store_dwordx2 v[86:87], v[20:21], off nt
	v_pk_fma_f32 v[20:21], v[20:21], v[32:33], v[54:55] op_sel_hi:[1,0,1]
	s_waitcnt vmcnt(15)
	global_store_dwordx2 v[88:89], v[20:21], off nt
	v_pk_fma_f32 v[20:21], v[20:21], v[34:35], v[56:57] op_sel_hi:[1,0,1]
	s_waitcnt vmcnt(15)
	global_store_dwordx2 v[90:91], v[20:21], off nt
	v_pk_fma_f32 v[20:21], v[20:21], v[36:37], v[58:59] op_sel_hi:[1,0,1]
	s_waitcnt vmcnt(15)
	global_store_dwordx2 v[92:93], v[20:21], off nt
	v_pk_fma_f32 v[20:21], v[20:21], v[38:39], v[60:61] op_sel_hi:[1,0,1]
	s_waitcnt vmcnt(15)
	global_store_dwordx2 v[94:95], v[20:21], off nt
	v_pk_fma_f32 v[20:21], v[20:21], v[40:41], v[62:63] op_sel_hi:[1,0,1]
	s_waitcnt vmcnt(15)
	global_store_dwordx2 v[96:97], v[20:21], off nt
	v_pk_fma_f32 v[20:21], v[20:21], v[22:23], v[64:65] op_sel_hi:[1,0,1]
	s_waitcnt vmcnt(15)
	global_store_dwordx2 v[98:99], v[20:21], off nt
	v_pk_fma_f32 v[20:21], v[20:21], v[16:17], v[66:67] op_sel_hi:[1,0,1]
	s_waitcnt vmcnt(15)
	global_store_dwordx2 v[100:101], v[20:21], off nt
	v_pk_fma_f32 v[20:21], v[20:21], v[14:15], v[68:69] op_sel_hi:[1,0,1]
	s_waitcnt vmcnt(15)
	global_store_dwordx2 v[102:103], v[20:21], off nt
	v_pk_fma_f32 v[20:21], v[20:21], v[12:13], v[70:71] op_sel_hi:[1,0,1]
	s_waitcnt vmcnt(15)
	global_store_dwordx2 v[104:105], v[20:21], off nt
	v_pk_fma_f32 v[20:21], v[20:21], v[10:11], v[72:73] op_sel_hi:[1,0,1]
	s_waitcnt vmcnt(15)
	global_store_dwordx2 v[106:107], v[20:21], off nt
	v_pk_fma_f32 v[20:21], v[20:21], v[8:9], v[74:75] op_sel_hi:[1,0,1]
	s_waitcnt vmcnt(15)
	global_store_dwordx2 v[108:109], v[20:21], off nt
	v_pk_fma_f32 v[20:21], v[20:21], v[6:7], v[76:77] op_sel_hi:[1,0,1]
	s_waitcnt vmcnt(15)
	global_store_dwordx2 v[110:111], v[20:21], off nt
	v_pk_fma_f32 v[20:21], v[20:21], v[0:1], v[78:79] op_sel_hi:[1,0,1]
	s_cbranch_scc0 .LBB0_303
	v_readlane_b32 s10, v253, 63
	v_and_b32_e32 v4, 7, v13
	v_and_b32_e32 v0, 63, v15
	v_add_u32_e32 v2, s10, v17
	v_ashrrev_i32_e32 v3, 31, v2
	v_lshlrev_b64 v[2:3], 9, v[2:3]
	v_lshlrev_b32_e32 v4, 6, v4
	v_or3_b32 v2, v2, v4, v0
	v_readlane_b32 s2, v252, 26
	v_lshlrev_b64 v[2:3], 9, v[2:3]
	v_lshl_add_u64 v[2:3], s[6:7], 0, v[2:3]
	v_add_u32_e32 v7, s2, v7
	s_mov_b32 s2, 0x1ffff
	v_and_b32_e32 v0, 0x1f8, v11
	v_cmp_lt_i32_e32 vcc, s2, v7
	v_readlane_b32 s2, v253, 12
	v_lshl_add_u64 v[2:3], v[2:3], 0, v[0:1]
	s_or_b64 s[8:9], vcc, s[8:9]
	v_add_u32_e32 v9, s2, v9
	v_readlane_b32 s11, v254, 0
	global_store_dwordx2 v[2:3], v[20:21], off nt
	s_andn2_b64 exec, exec, s[8:9]
	s_cbranch_execnz .LBB0_302

.LBB0_322:
	s_or_b64 exec, exec, s[4:5]
	s_waitcnt lgkmcnt(1)
	v_sub_f32_e32 v3, v3, v4
	v_mul_f32_e32 v3, 0x3fb8aa3b, v3
	v_exp_f32_e32 v3, v3
	v_and_b32_e32 v28, 0x7f, v18
	s_waitcnt lgkmcnt(0)
	s_barrier
	v_mul_f32_e32 v2, v2, v3
	ds_write_b32 v0, v2
	v_or_b32_e32 v0, s2, v28
	v_readlane_b32 s8, v253, 46
	v_ashrrev_i32_e32 v2, 4, v18
	v_lshlrev_b32_e32 v0, 11, v0
	v_readlane_b32 s9, v253, 47
	v_and_b32_e32 v6, -8, v2
	s_lshl_b32 s2, s7, 8
	v_lshl_add_u64 v[24:25], s[8:9], 0, v[0:1]
	v_ashrrev_i32_e32 v7, 31, v6
	v_lshl_add_u64 v[20:21], v[24:25], 0, s[2:3]
	v_lshlrev_b64 v[26:27], 1, v[6:7]
	v_lshl_add_u64 v[2:3], v[20:21], 0, v[26:27]
	s_waitcnt lgkmcnt(0)
	s_barrier
	v_bfe_u32 v0, v201, 3, 2
	v_lshrrev_b32_e32 v2, 5, v201
	v_lshl_add_u32 v0, v0, 7, v2
	v_lshlrev_b32_e32 v0, 2, v0
	v_add_u32_e32 v0, 0x1a000, v0
	ds_read_b32 v4, v0
	ds_read_b32 v5, v0 offset:64
	ds_read_b32 v6, v0 offset:128
	ds_read_b32 v7, v0 offset:192
	ds_read_b32 v8, v0 offset:256
	ds_read_b32 v9, v0 offset:320
	ds_read_b32 v10, v0 offset:384
	ds_read_b32 v11, v0 offset:448
	v_lshrrev_b32_e32 v12, 7, v201
	v_lshlrev_b32_e32 v12, 11, v12
	v_bfe_u32 v13, v201, 2, 2
	v_lshl_add_u32 v12, v13, 9, v12
	v_bfe_u32 v13, v201, 4, 3
	v_lshl_add_u32 v12, v13, 6, v12
	v_and_b32_e32 v13, 3, v201
	v_bfe_u32 v14, v201, 6, 2
	v_xor_b32_e32 v13, v13, v14
	v_lshl_add_u32 v12, v13, 4, v12
	v_bfe_u32 v13, v201, 4, 1
	v_lshlrev_b32_e32 v15, 15, v13
	v_lshrrev_b32_e32 v13, 8, v201
	v_lshl_add_u32 v15, v13, 11, v15
	v_bfe_u32 v13, v201, 2, 2
	v_lshl_add_u32 v15, v13, 9, v15
	v_bfe_u32 v13, v201, 5, 3
	v_lshl_add_u32 v15, v13, 6, v15
	v_and_b32_e32 v13, 3, v201
	v_bfe_u32 v14, v201, 7, 2
	v_xor_b32_e32 v13, v13, v14
	v_lshl_add_u32 v15, v13, 4, v15
	v_add_u32_e32 v15, 0x8800, v15
	s_waitcnt vmcnt(11)
	ds_write_b128 v12, v[96:99]
	s_waitcnt vmcnt(10)
	ds_write_b128 v12, v[100:103] offset:8192
	s_waitcnt vmcnt(9)
	ds_write_b128 v12, v[104:107] offset:16384
	s_waitcnt vmcnt(8)
	ds_write_b128 v12, v[108:111] offset:24576
	v_and_b32_e32 v80, 63, v201
	v_lshrrev_b32_e32 v81, 4, v80
	v_and_b32_e32 v82, 15, v80
	v_lshrrev_b32_e32 v83, 2, v82
	v_and_b32_e32 v82, 3, v82
	v_lshlrev_b32_e32 v80, 11, v81
	v_lshl_add_u32 v80, v83, 6, v80
	v_and_b32_e32 v83, 1, v82
	v_lshl_add_u32 v80, v83, 3, v80
	v_and_b32_e32 v81, 1, v81
	v_lshrrev_b32_e32 v82, 1, v82
	v_xor_b32_e32 v83, 1, v81
	v_xor_b32_e32 v92, 1, v82
	v_lshl_add_u32 v93, v81, 5, v80
	v_lshl_add_u32 v94, v83, 5, v80
	v_lshl_add_u32 v84, v82, 4, v93
	v_lshl_add_u32 v85, v92, 4, v93
	v_add_u32_e32 v85, 0x100, v85
	v_lshl_add_u32 v86, v82, 4, v94
	v_lshl_add_u32 v87, v92, 4, v94
	v_add_u32_e32 v87, 0x100, v87
	v_lshrrev_b32_e32 v80, 6, v201
	v_lshrrev_b32_e32 v81, 2, v80
	v_and_b32_e32 v80, 3, v80
	v_lshlrev_b32_e32 v81, 15, v81
	v_lshl_add_u32 v81, v80, 9, v81
	v_add_u32_e32 v81, 0x8800, v81
	v_add_u32_e32 v88, v84, v81
	v_add_u32_e32 v89, v85, v81
	v_add_u32_e32 v90, v86, v81
	v_add_u32_e32 v91, v87, v81
	s_waitcnt lgkmcnt(0)
	s_waitcnt vmcnt(7)
	v_lshlrev_b32_e32 v16, 16, v112
	v_and_b32_e32 v17, 0xffff0000, v112
	v_mul_f32_e32 v16, v4, v16
	v_mul_f32_e32 v17, v4, v17
	v_cvt_pk_bf16_f32 v20, v16, v17
	v_lshlrev_b32_e32 v16, 16, v113
	v_and_b32_e32 v17, 0xffff0000, v113
	v_mul_f32_e32 v16, v4, v16
	v_mul_f32_e32 v17, v4, v17
	v_cvt_pk_bf16_f32 v21, v16, v17
	v_lshlrev_b32_e32 v16, 16, v114
	v_and_b32_e32 v17, 0xffff0000, v114
	v_mul_f32_e32 v16, v4, v16
	v_mul_f32_e32 v17, v4, v17
	v_cvt_pk_bf16_f32 v22, v16, v17
	v_lshlrev_b32_e32 v16, 16, v115
	v_and_b32_e32 v17, 0xffff0000, v115
	v_mul_f32_e32 v16, v4, v16
	v_mul_f32_e32 v17, v4, v17
	v_cvt_pk_bf16_f32 v23, v16, v17
	ds_write_b128 v15, v[20:23]
	s_waitcnt vmcnt(6)
	v_lshlrev_b32_e32 v16, 16, v116
	v_and_b32_e32 v17, 0xffff0000, v116
	v_mul_f32_e32 v16, v5, v16
	v_mul_f32_e32 v17, v5, v17
	v_cvt_pk_bf16_f32 v24, v16, v17
	v_lshlrev_b32_e32 v16, 16, v117
	v_and_b32_e32 v17, 0xffff0000, v117
	v_mul_f32_e32 v16, v5, v16
	v_mul_f32_e32 v17, v5, v17
	v_cvt_pk_bf16_f32 v25, v16, v17
	v_lshlrev_b32_e32 v16, 16, v118
	v_and_b32_e32 v17, 0xffff0000, v118
	v_mul_f32_e32 v16, v5, v16
	v_mul_f32_e32 v17, v5, v17
	v_cvt_pk_bf16_f32 v26, v16, v17
	v_lshlrev_b32_e32 v16, 16, v119
	v_and_b32_e32 v17, 0xffff0000, v119
	v_mul_f32_e32 v16, v5, v16
	v_mul_f32_e32 v17, v5, v17
	v_cvt_pk_bf16_f32 v27, v16, v17
	ds_write_b128 v15, v[24:27] offset:4096
	s_waitcnt vmcnt(5)
	v_lshlrev_b32_e32 v16, 16, v120
	v_and_b32_e32 v17, 0xffff0000, v120
	v_mul_f32_e32 v16, v6, v16
	v_mul_f32_e32 v17, v6, v17
	v_cvt_pk_bf16_f32 v20, v16, v17
	v_lshlrev_b32_e32 v16, 16, v121
	v_and_b32_e32 v17, 0xffff0000, v121
	v_mul_f32_e32 v16, v6, v16
	v_mul_f32_e32 v17, v6, v17
	v_cvt_pk_bf16_f32 v21, v16, v17
	v_lshlrev_b32_e32 v16, 16, v122
	v_and_b32_e32 v17, 0xffff0000, v122
	v_mul_f32_e32 v16, v6, v16
	v_mul_f32_e32 v17, v6, v17
	v_cvt_pk_bf16_f32 v22, v16, v17
	v_lshlrev_b32_e32 v16, 16, v123
	v_and_b32_e32 v17, 0xffff0000, v123
	v_mul_f32_e32 v16, v6, v16
	v_mul_f32_e32 v17, v6, v17
	v_cvt_pk_bf16_f32 v23, v16, v17
	ds_write_b128 v15, v[20:23] offset:8192
	s_waitcnt vmcnt(4)
	v_lshlrev_b32_e32 v16, 16, v124
	v_and_b32_e32 v17, 0xffff0000, v124
	v_mul_f32_e32 v16, v7, v16
	v_mul_f32_e32 v17, v7, v17
	v_cvt_pk_bf16_f32 v24, v16, v17
	v_lshlrev_b32_e32 v16, 16, v125
	v_and_b32_e32 v17, 0xffff0000, v125
	v_mul_f32_e32 v16, v7, v16
	v_mul_f32_e32 v17, v7, v17
	v_cvt_pk_bf16_f32 v25, v16, v17
	v_lshlrev_b32_e32 v16, 16, v126
	v_and_b32_e32 v17, 0xffff0000, v126
	v_mul_f32_e32 v16, v7, v16
	v_mul_f32_e32 v17, v7, v17
	v_cvt_pk_bf16_f32 v26, v16, v17
	v_lshlrev_b32_e32 v16, 16, v127
	v_and_b32_e32 v17, 0xffff0000, v127
	v_mul_f32_e32 v16, v7, v16
	v_mul_f32_e32 v17, v7, v17
	v_cvt_pk_bf16_f32 v27, v16, v17
	ds_write_b128 v15, v[24:27] offset:12288
	s_waitcnt vmcnt(3)
	v_lshlrev_b32_e32 v16, 16, v128
	v_and_b32_e32 v17, 0xffff0000, v128
	v_mul_f32_e32 v16, v8, v16
	v_mul_f32_e32 v17, v8, v17
	v_cvt_pk_bf16_f32 v20, v16, v17
	v_lshlrev_b32_e32 v16, 16, v129
	v_and_b32_e32 v17, 0xffff0000, v129
	v_mul_f32_e32 v16, v8, v16
	v_mul_f32_e32 v17, v8, v17
	v_cvt_pk_bf16_f32 v21, v16, v17
	v_lshlrev_b32_e32 v16, 16, v130
	v_and_b32_e32 v17, 0xffff0000, v130
	v_mul_f32_e32 v16, v8, v16
	v_mul_f32_e32 v17, v8, v17
	v_cvt_pk_bf16_f32 v22, v16, v17
	v_lshlrev_b32_e32 v16, 16, v131
	v_and_b32_e32 v17, 0xffff0000, v131
	v_mul_f32_e32 v16, v8, v16
	v_mul_f32_e32 v17, v8, v17
	v_cvt_pk_bf16_f32 v23, v16, v17
	ds_write_b128 v15, v[20:23] offset:16384
	s_waitcnt vmcnt(2)
	v_lshlrev_b32_e32 v16, 16, v132
	v_and_b32_e32 v17, 0xffff0000, v132
	v_mul_f32_e32 v16, v9, v16
	v_mul_f32_e32 v17, v9, v17
	v_cvt_pk_bf16_f32 v24, v16, v17
	v_lshlrev_b32_e32 v16, 16, v133
	v_and_b32_e32 v17, 0xffff0000, v133
	v_mul_f32_e32 v16, v9, v16
	v_mul_f32_e32 v17, v9, v17
	v_cvt_pk_bf16_f32 v25, v16, v17
	v_lshlrev_b32_e32 v16, 16, v134
	v_and_b32_e32 v17, 0xffff0000, v134
	v_mul_f32_e32 v16, v9, v16
	v_mul_f32_e32 v17, v9, v17
	v_cvt_pk_bf16_f32 v26, v16, v17
	v_lshlrev_b32_e32 v16, 16, v135
	v_and_b32_e32 v17, 0xffff0000, v135
	v_mul_f32_e32 v16, v9, v16
	v_mul_f32_e32 v17, v9, v17
	v_cvt_pk_bf16_f32 v27, v16, v17
	ds_write_b128 v15, v[24:27] offset:20480
	s_waitcnt vmcnt(1)
	v_lshlrev_b32_e32 v16, 16, v136
	v_and_b32_e32 v17, 0xffff0000, v136
	v_mul_f32_e32 v16, v10, v16
	v_mul_f32_e32 v17, v10, v17
	v_cvt_pk_bf16_f32 v20, v16, v17
	v_lshlrev_b32_e32 v16, 16, v137
	v_and_b32_e32 v17, 0xffff0000, v137
	v_mul_f32_e32 v16, v10, v16
	v_mul_f32_e32 v17, v10, v17
	v_cvt_pk_bf16_f32 v21, v16, v17
	v_lshlrev_b32_e32 v16, 16, v138
	v_and_b32_e32 v17, 0xffff0000, v138
	v_mul_f32_e32 v16, v10, v16
	v_mul_f32_e32 v17, v10, v17
	v_cvt_pk_bf16_f32 v22, v16, v17
	v_lshlrev_b32_e32 v16, 16, v139
	v_and_b32_e32 v17, 0xffff0000, v139
	v_mul_f32_e32 v16, v10, v16
	v_mul_f32_e32 v17, v10, v17
	v_cvt_pk_bf16_f32 v23, v16, v17
	ds_write_b128 v15, v[20:23] offset:24576
	s_waitcnt vmcnt(0)
	v_lshlrev_b32_e32 v16, 16, v140
	v_and_b32_e32 v17, 0xffff0000, v140
	v_mul_f32_e32 v16, v11, v16
	v_mul_f32_e32 v17, v11, v17
	v_cvt_pk_bf16_f32 v24, v16, v17
	v_lshlrev_b32_e32 v16, 16, v141
	v_and_b32_e32 v17, 0xffff0000, v141
	v_mul_f32_e32 v16, v11, v16
	v_mul_f32_e32 v17, v11, v17
	v_cvt_pk_bf16_f32 v25, v16, v17
	v_lshlrev_b32_e32 v16, 16, v142
	v_and_b32_e32 v17, 0xffff0000, v142
	v_mul_f32_e32 v16, v11, v16
	v_mul_f32_e32 v17, v11, v17
	v_cvt_pk_bf16_f32 v26, v16, v17
	v_lshlrev_b32_e32 v16, 16, v143
	v_and_b32_e32 v17, 0xffff0000, v143
	v_mul_f32_e32 v16, v11, v16
	v_mul_f32_e32 v17, v11, v17
	v_cvt_pk_bf16_f32 v27, v16, v17
	ds_write_b128 v15, v[24:27] offset:28672
	s_waitcnt lgkmcnt(0)
	s_barrier
	ds_read_b64_tr_b16 v[96:97], v88
	ds_read_b64_tr_b16 v[98:99], v89
	ds_read_b64_tr_b16 v[100:101], v90
	ds_read_b64_tr_b16 v[102:103], v91
	ds_read_b64_tr_b16 v[104:105], v84
	ds_read_b64_tr_b16 v[106:107], v85
	ds_read_b64_tr_b16 v[108:109], v86
	ds_read_b64_tr_b16 v[110:111], v87
	ds_read_b64_tr_b16 v[112:113], v84 offset:512
	ds_read_b64_tr_b16 v[114:115], v85 offset:512
	s_waitcnt lgkmcnt(5)
	ds_read_b64_tr_b16 v[116:117], v86 offset:512
	ds_read_b64_tr_b16 v[118:119], v87 offset:512
	ds_read_b64_tr_b16 v[120:121], v84 offset:1024
	ds_read_b64_tr_b16 v[122:123], v85 offset:1024
	ds_read_b64_tr_b16 v[124:125], v86 offset:1024
	ds_read_b64_tr_b16 v[126:127], v87 offset:1024
	ds_read_b64_tr_b16 v[128:129], v84 offset:1536
	ds_read_b64_tr_b16 v[130:131], v85 offset:1536
	ds_read_b64_tr_b16 v[132:133], v86 offset:1536
	ds_read_b64_tr_b16 v[134:135], v87 offset:1536
	s_waitcnt lgkmcnt(0)
	ds_read_b64_tr_b16 v[136:137], v88 offset:8192
	ds_read_b64_tr_b16 v[138:139], v89 offset:8192
	ds_read_b64_tr_b16 v[140:141], v90 offset:8192
	ds_read_b64_tr_b16 v[142:143], v91 offset:8192
	ds_read_b64_tr_b16 v[144:145], v84 offset:8192
	ds_read_b64_tr_b16 v[146:147], v85 offset:8192
	ds_read_b64_tr_b16 v[148:149], v86 offset:8192
	ds_read_b64_tr_b16 v[150:151], v87 offset:8192
	ds_read_b64_tr_b16 v[152:153], v84 offset:8704
	ds_read_b64_tr_b16 v[154:155], v85 offset:8704
	v_mfma_f32_16x16x32_bf16 v[16:19], v[104:107], v[96:99], 0
	v_mfma_f32_16x16x32_bf16 v[20:23], v[108:111], v[96:99], 0
	v_mfma_f32_16x16x32_bf16 v[24:27], v[112:115], v[96:99], 0
	v_mfma_f32_16x16x32_bf16 v[28:31], v[116:119], v[96:99], 0
	v_mfma_f32_16x16x32_bf16 v[32:35], v[120:123], v[96:99], 0
	v_mfma_f32_16x16x32_bf16 v[36:39], v[124:127], v[96:99], 0
	v_mfma_f32_16x16x32_bf16 v[40:43], v[128:131], v[96:99], 0
	v_mfma_f32_16x16x32_bf16 v[44:47], v[132:135], v[96:99], 0
	s_waitcnt lgkmcnt(5)
	ds_read_b64_tr_b16 v[156:157], v86 offset:8704
	ds_read_b64_tr_b16 v[158:159], v87 offset:8704
	ds_read_b64_tr_b16 v[160:161], v84 offset:9216
	ds_read_b64_tr_b16 v[162:163], v85 offset:9216
	ds_read_b64_tr_b16 v[164:165], v86 offset:9216
	ds_read_b64_tr_b16 v[166:167], v87 offset:9216
	ds_read_b64_tr_b16 v[168:169], v84 offset:9728
	ds_read_b64_tr_b16 v[170:171], v85 offset:9728
	ds_read_b64_tr_b16 v[172:173], v86 offset:9728
	ds_read_b64_tr_b16 v[174:175], v87 offset:9728
	v_mfma_f32_16x16x32_bf16 v[48:51], v[104:107], v[100:103], 0
	v_mfma_f32_16x16x32_bf16 v[52:55], v[108:111], v[100:103], 0
	v_mfma_f32_16x16x32_bf16 v[56:59], v[112:115], v[100:103], 0
	v_mfma_f32_16x16x32_bf16 v[60:63], v[116:119], v[100:103], 0
	v_mfma_f32_16x16x32_bf16 v[64:67], v[120:123], v[100:103], 0
	v_mfma_f32_16x16x32_bf16 v[68:71], v[124:127], v[100:103], 0
	v_mfma_f32_16x16x32_bf16 v[72:75], v[128:131], v[100:103], 0
	v_mfma_f32_16x16x32_bf16 v[76:79], v[132:135], v[100:103], 0
	s_waitcnt lgkmcnt(0)
	ds_read_b64_tr_b16 v[96:97], v88 offset:16384
	ds_read_b64_tr_b16 v[98:99], v89 offset:16384
	ds_read_b64_tr_b16 v[100:101], v90 offset:16384
	ds_read_b64_tr_b16 v[102:103], v91 offset:16384
	ds_read_b64_tr_b16 v[104:105], v84 offset:16384
	ds_read_b64_tr_b16 v[106:107], v85 offset:16384
	ds_read_b64_tr_b16 v[108:109], v86 offset:16384
	ds_read_b64_tr_b16 v[110:111], v87 offset:16384
	ds_read_b64_tr_b16 v[112:113], v84 offset:16896
	ds_read_b64_tr_b16 v[114:115], v85 offset:16896
	v_mfma_f32_16x16x32_bf16 v[16:19], v[144:147], v[136:139], v[16:19]
	v_mfma_f32_16x16x32_bf16 v[20:23], v[148:151], v[136:139], v[20:23]
	v_mfma_f32_16x16x32_bf16 v[24:27], v[152:155], v[136:139], v[24:27]
	v_mfma_f32_16x16x32_bf16 v[28:31], v[156:159], v[136:139], v[28:31]
	v_mfma_f32_16x16x32_bf16 v[32:35], v[160:163], v[136:139], v[32:35]
	v_mfma_f32_16x16x32_bf16 v[36:39], v[164:167], v[136:139], v[36:39]
	v_mfma_f32_16x16x32_bf16 v[40:43], v[168:171], v[136:139], v[40:43]
	v_mfma_f32_16x16x32_bf16 v[44:47], v[172:175], v[136:139], v[44:47]
	s_waitcnt lgkmcnt(5)
	ds_read_b64_tr_b16 v[116:117], v86 offset:16896
	ds_read_b64_tr_b16 v[118:119], v87 offset:16896
	ds_read_b64_tr_b16 v[120:121], v84 offset:17408
	ds_read_b64_tr_b16 v[122:123], v85 offset:17408
	ds_read_b64_tr_b16 v[124:125], v86 offset:17408
	ds_read_b64_tr_b16 v[126:127], v87 offset:17408
	ds_read_b64_tr_b16 v[128:129], v84 offset:17920
	ds_read_b64_tr_b16 v[130:131], v85 offset:17920
	ds_read_b64_tr_b16 v[132:133], v86 offset:17920
	ds_read_b64_tr_b16 v[134:135], v87 offset:17920
	v_mfma_f32_16x16x32_bf16 v[48:51], v[144:147], v[140:143], v[48:51]
	v_mfma_f32_16x16x32_bf16 v[52:55], v[148:151], v[140:143], v[52:55]
	v_mfma_f32_16x16x32_bf16 v[56:59], v[152:155], v[140:143], v[56:59]
	v_mfma_f32_16x16x32_bf16 v[60:63], v[156:159], v[140:143], v[60:63]
	v_mfma_f32_16x16x32_bf16 v[64:67], v[160:163], v[140:143], v[64:67]
	v_mfma_f32_16x16x32_bf16 v[68:71], v[164:167], v[140:143], v[68:71]
	v_mfma_f32_16x16x32_bf16 v[72:75], v[168:171], v[140:143], v[72:75]
	v_mfma_f32_16x16x32_bf16 v[76:79], v[172:175], v[140:143], v[76:79]
	s_waitcnt lgkmcnt(0)
	ds_read_b64_tr_b16 v[136:137], v88 offset:24576
	ds_read_b64_tr_b16 v[138:139], v89 offset:24576
	ds_read_b64_tr_b16 v[140:141], v90 offset:24576
	ds_read_b64_tr_b16 v[142:143], v91 offset:24576
	ds_read_b64_tr_b16 v[144:145], v84 offset:24576
	ds_read_b64_tr_b16 v[146:147], v85 offset:24576
	ds_read_b64_tr_b16 v[148:149], v86 offset:24576
	ds_read_b64_tr_b16 v[150:151], v87 offset:24576
	ds_read_b64_tr_b16 v[152:153], v84 offset:25088
	ds_read_b64_tr_b16 v[154:155], v85 offset:25088
	v_mfma_f32_16x16x32_bf16 v[16:19], v[104:107], v[96:99], v[16:19]
	v_mfma_f32_16x16x32_bf16 v[20:23], v[108:111], v[96:99], v[20:23]
	v_mfma_f32_16x16x32_bf16 v[24:27], v[112:115], v[96:99], v[24:27]
	v_mfma_f32_16x16x32_bf16 v[28:31], v[116:119], v[96:99], v[28:31]
	v_mfma_f32_16x16x32_bf16 v[32:35], v[120:123], v[96:99], v[32:35]
	v_mfma_f32_16x16x32_bf16 v[36:39], v[124:127], v[96:99], v[36:39]
	v_mfma_f32_16x16x32_bf16 v[40:43], v[128:131], v[96:99], v[40:43]
	v_mfma_f32_16x16x32_bf16 v[44:47], v[132:135], v[96:99], v[44:47]
	s_waitcnt lgkmcnt(5)
	ds_read_b64_tr_b16 v[156:157], v86 offset:25088
	ds_read_b64_tr_b16 v[158:159], v87 offset:25088
	ds_read_b64_tr_b16 v[160:161], v84 offset:25600
	ds_read_b64_tr_b16 v[162:163], v85 offset:25600
	ds_read_b64_tr_b16 v[164:165], v86 offset:25600
	ds_read_b64_tr_b16 v[166:167], v87 offset:25600
	ds_read_b64_tr_b16 v[168:169], v84 offset:26112
	ds_read_b64_tr_b16 v[170:171], v85 offset:26112
	ds_read_b64_tr_b16 v[172:173], v86 offset:26112
	ds_read_b64_tr_b16 v[174:175], v87 offset:26112
	v_mfma_f32_16x16x32_bf16 v[48:51], v[104:107], v[100:103], v[48:51]
	v_mfma_f32_16x16x32_bf16 v[52:55], v[108:111], v[100:103], v[52:55]
	v_mfma_f32_16x16x32_bf16 v[56:59], v[112:115], v[100:103], v[56:59]
	v_mfma_f32_16x16x32_bf16 v[60:63], v[116:119], v[100:103], v[60:63]
	v_mfma_f32_16x16x32_bf16 v[64:67], v[120:123], v[100:103], v[64:67]
	v_mfma_f32_16x16x32_bf16 v[68:71], v[124:127], v[100:103], v[68:71]
	v_mfma_f32_16x16x32_bf16 v[72:75], v[128:131], v[100:103], v[72:75]
	v_mfma_f32_16x16x32_bf16 v[76:79], v[132:135], v[100:103], v[76:79]
	s_waitcnt lgkmcnt(0)
	v_mfma_f32_16x16x32_bf16 v[16:19], v[144:147], v[136:139], v[16:19]
	v_mfma_f32_16x16x32_bf16 v[20:23], v[148:151], v[136:139], v[20:23]
	v_mfma_f32_16x16x32_bf16 v[24:27], v[152:155], v[136:139], v[24:27]
	v_mfma_f32_16x16x32_bf16 v[28:31], v[156:159], v[136:139], v[28:31]
	v_mfma_f32_16x16x32_bf16 v[32:35], v[160:163], v[136:139], v[32:35]
	v_mfma_f32_16x16x32_bf16 v[36:39], v[164:167], v[136:139], v[36:39]
	v_mfma_f32_16x16x32_bf16 v[40:43], v[168:171], v[136:139], v[40:43]
	v_mfma_f32_16x16x32_bf16 v[44:47], v[172:175], v[136:139], v[44:47]
	v_mfma_f32_16x16x32_bf16 v[48:51], v[144:147], v[140:143], v[48:51]
	v_mfma_f32_16x16x32_bf16 v[52:55], v[148:151], v[140:143], v[52:55]
	v_mfma_f32_16x16x32_bf16 v[56:59], v[152:155], v[140:143], v[56:59]
	v_mfma_f32_16x16x32_bf16 v[60:63], v[156:159], v[140:143], v[60:63]
	v_mfma_f32_16x16x32_bf16 v[64:67], v[160:163], v[140:143], v[64:67]
	v_mfma_f32_16x16x32_bf16 v[68:71], v[164:167], v[140:143], v[68:71]
	v_mfma_f32_16x16x32_bf16 v[72:75], v[168:171], v[140:143], v[72:75]
	v_mfma_f32_16x16x32_bf16 v[76:79], v[172:175], v[140:143], v[76:79]
	v_readlane_b32 s4, v254, 9
	v_readlane_b32 s5, v254, 10
	v_lshrrev_b32_e32 v0, 6, v201
	v_lshlrev_b32_e32 v0, 5, v0
	v_and_b32_e32 v2, 15, v201
	v_add_u32_e32 v0, v0, v2
	v_lshlrev_b32_e32 v0, 9, v0
	v_bfe_u32 v2, v201, 4, 2
	v_lshl_add_u32 v0, v2, 4, v0
	s_lshl_b32 s8, s6, 15
	s_mov_b32 s9, 0
	s_mov_b32 s98, 0x2000
	s_mov_b32 s99, 0
	v_lshl_add_u64 v[10:11], s[4:5], 0, v[0:1]
	v_lshl_add_u64 v[10:11], v[10:11], 0, s[8:9]
	v_lshl_add_u64 v[12:13], v[10:11], 0, s[98:99]
	s_nop 7
	s_nop 7
	s_nop 7
	s_nop 7
	global_store_dwordx4 v[10:11], v[16:19], off nt
	global_store_dwordx4 v[10:11], v[20:23], off offset:64 nt
	global_store_dwordx4 v[10:11], v[24:27], off offset:128 nt
	global_store_dwordx4 v[10:11], v[28:31], off offset:192 nt
	global_store_dwordx4 v[10:11], v[32:35], off offset:256 nt
	global_store_dwordx4 v[10:11], v[36:39], off offset:320 nt
	global_store_dwordx4 v[10:11], v[40:43], off offset:384 nt
	global_store_dwordx4 v[10:11], v[44:47], off offset:448 nt
	global_store_dwordx4 v[12:13], v[48:51], off nt
	global_store_dwordx4 v[12:13], v[52:55], off offset:64 nt
	global_store_dwordx4 v[12:13], v[56:59], off offset:128 nt
	global_store_dwordx4 v[12:13], v[60:63], off offset:192 nt
	global_store_dwordx4 v[12:13], v[64:67], off offset:256 nt
	global_store_dwordx4 v[12:13], v[68:71], off offset:320 nt
	global_store_dwordx4 v[12:13], v[72:75], off offset:384 nt
	global_store_dwordx4 v[12:13], v[76:79], off offset:448 nt
	s_mov_b64 s[4:5], 0
